# v52 + removed 32 redundant canonicalizing v_max per key tile in the indexer score loop
# speedup vs baseline: 1.0020x; 1.0020x over previous
.LBB0_649:
	s_barrier
	s_waitcnt vmcnt(2)
	ds_write_b128 v0, v[70:73]
	s_waitcnt lgkmcnt(0)
	s_barrier
	ds_read_b128 v[2:5], v126
	ds_read_b128 v[70:73], v126 offset:32
	s_waitcnt lgkmcnt(1)
	v_mfma_f32_32x32x16_bf16 v[18:33], v[34:37], v[2:5], 0
	ds_read_b128 v[2:5], v126 offset:4608
	ds_read_b128 v[128:131], v126 offset:4640
	s_add_i32 s6, s1, 4
	s_min_u32 s6, s6, s0
	s_lshl_b32 s52, s6, 6
	s_lshl_b64 s[6:7], s[52:53], 7
	s_add_i32 s1, s1, 1
	s_cmp_lg_u32 s0, s1
	s_waitcnt lgkmcnt(1)
	v_mfma_f32_32x32x16_bf16 v[2:17], v[34:37], v[2:5], 0
	v_mfma_f32_32x32x16_bf16 v[18:33], v[38:41], v[70:73], v[18:33]
	s_waitcnt lgkmcnt(0)
	v_mfma_f32_32x32x16_bf16 v[2:17], v[38:41], v[128:131], v[2:17]
	ds_read_b128 v[70:73], v126 offset:64
	ds_read_b128 v[128:131], v126 offset:96
	s_waitcnt lgkmcnt(1)
	v_mfma_f32_32x32x16_bf16 v[18:33], v[42:45], v[70:73], v[18:33]
	ds_read_b128 v[70:73], v126 offset:4672
	ds_read_b128 v[132:135], v126 offset:4704
	s_waitcnt lgkmcnt(1)
	v_mfma_f32_32x32x16_bf16 v[2:17], v[42:45], v[70:73], v[2:17]
	s_waitcnt vmcnt(1)
	v_mov_b64_e32 v[72:73], v[68:69]
	v_mov_b64_e32 v[70:71], v[66:67]
	s_waitcnt vmcnt(0)
	v_mov_b64_e32 v[66:67], v[74:75]
	v_mov_b64_e32 v[68:69], v[76:77]
	v_lshl_add_u64 v[74:75], v[90:91], 0, s[6:7]
	global_load_dwordx4 v[74:77], v[74:75], off
	v_mfma_f32_32x32x16_bf16 v[18:33], v[46:49], v[128:131], v[18:33]
	s_waitcnt lgkmcnt(0)
	v_mfma_f32_32x32x16_bf16 v[2:17], v[46:49], v[132:135], v[2:17]
	s_nop 9
	v_max_f32_e32 v18, 0, v18
	v_max_f32_e32 v26, 0, v26
	v_max_f32_e32 v2, 0, v2
	v_max_f32_e32 v10, 0, v10
	v_max_f32_e32 v19, 0, v19
	v_max_f32_e32 v27, 0, v27
	v_max_f32_e32 v3, 0, v3
	v_max_f32_e32 v11, 0, v11
	v_fma_f32 v18, v50, v18, 0
	v_fma_f32 v26, v58, v26, 0
	v_fma_f32 v2, v50, v2, 0
	v_fma_f32 v10, v58, v10, 0
	v_max_f32_e32 v20, 0, v20
	v_max_f32_e32 v28, 0, v28
	v_max_f32_e32 v4, 0, v4
	v_max_f32_e32 v12, 0, v12
	v_fmac_f32_e32 v18, v51, v19
	v_fmac_f32_e32 v26, v59, v27
	v_fmac_f32_e32 v2, v51, v3
	v_fmac_f32_e32 v10, v59, v11
	v_max_f32_e32 v21, 0, v21
	v_max_f32_e32 v29, 0, v29
	v_max_f32_e32 v5, 0, v5
	v_max_f32_e32 v13, 0, v13
	v_fmac_f32_e32 v18, v52, v20
	v_fmac_f32_e32 v26, v60, v28
	v_fmac_f32_e32 v2, v52, v4
	v_fmac_f32_e32 v10, v60, v12
	v_max_f32_e32 v22, 0, v22
	v_max_f32_e32 v30, 0, v30
	v_max_f32_e32 v6, 0, v6
	v_max_f32_e32 v14, 0, v14
	v_fmac_f32_e32 v18, v53, v21
	v_fmac_f32_e32 v26, v61, v29
	v_fmac_f32_e32 v2, v53, v5
	v_fmac_f32_e32 v10, v61, v13
	v_max_f32_e32 v23, 0, v23
	v_max_f32_e32 v31, 0, v31
	v_max_f32_e32 v7, 0, v7
	v_max_f32_e32 v15, 0, v15
	v_fmac_f32_e32 v18, v54, v22
	v_fmac_f32_e32 v26, v62, v30
	v_fmac_f32_e32 v2, v54, v6
	v_fmac_f32_e32 v10, v62, v14
	v_max_f32_e32 v24, 0, v24
	v_max_f32_e32 v32, 0, v32
	v_max_f32_e32 v8, 0, v8
	v_max_f32_e32 v16, 0, v16
	v_fmac_f32_e32 v18, v55, v23
	v_fmac_f32_e32 v26, v63, v31
	v_fmac_f32_e32 v2, v55, v7
	v_fmac_f32_e32 v10, v63, v15
	v_max_f32_e32 v25, 0, v25
	v_max_f32_e32 v33, 0, v33
	v_max_f32_e32 v9, 0, v9
	v_max_f32_e32 v17, 0, v17
	v_fmac_f32_e32 v18, v56, v24
	v_fmac_f32_e32 v26, v64, v32
	v_fmac_f32_e32 v2, v56, v8
	v_fmac_f32_e32 v10, v64, v16
	v_fmac_f32_e32 v18, v57, v25
	v_fmac_f32_e32 v26, v65, v33
	v_fmac_f32_e32 v2, v57, v9
	v_fmac_f32_e32 v10, v65, v17
	s_nop 1
	v_permlane32_swap_b32_e32 v18, v26
	v_permlane32_swap_b32_e32 v2, v10
	v_add_f32_e32 v3, v18, v26
	v_add_f32_e32 v2, v2, v10
	ds_write2_b32 v127, v3, v2 offset1:32
	v_add_u32_e32 v127, 0x100, v127
	s_cbranch_scc1 .LBB0_649
	s_mov_b32 s52, 0
	s_mov_b64 s[64:65], -1
	s_branch .LBB0_652
